# retention scan: the two virtual blocks of a workgroup share one K'^T LDS tile per step (each loads and stores half of it), halving K'^T global loads and LDS writes
# baseline (speedup 1.0000x reference)
.LBB0_379:
	s_and_b64 vcc, exec, s[0:1]
	s_cbranch_vccz .LBB0_463
	v_bfe_u32 v100, v147, 2, 1
	v_and_b32_e32 v221, 1, v147
	v_mov_b32_e32 v219, 0
	v_mov_b32_e32 v223, 0
	s_nop 0
	v_mul_u32_u24_e32 v220, 0x4400, v221
	v_lshlrev_b32_e32 v218, 15, v221
	v_lshlrev_b32_e32 v222, 19, v221
	v_mul_u32_u24_e32 v221, 0x12000, v221
	s_add_i32 s0, 0, 0x24048
	s_add_i32 s1, 0, 0x24050
	v_mov_b32_e32 v0, s1
	v_mov_b32_e32 v1, s0
	v_cmp_eq_u32_e64 s[0:1], 0, v100
	v_bfe_u32 v2, v147, 3, 2
	v_mov_b32_e32 v137, 0
	v_cndmask_b32_e64 v0, v0, v1, s[0:1]
	ds_read_b64 v[0:1], v0
	v_lshlrev_b32_e32 v2, 2, v2
	v_mov_b32_e32 v3, v137
	s_add_i32 s12, 0, 0x240a8
	v_ashrrev_i32_e32 v5, 3, v147
	s_waitcnt lgkmcnt(0)
	v_lshl_add_u64 v[0:1], v[0:1], 0, v[2:3]
	global_load_dword v44, v[0:1], off
	v_and_b32_e32 v1, 4, v147
	v_lshrrev_b32_e32 v0, 3, v147
	v_cmp_ne_u32_e64 s[6:7], 0, v1
	v_mov_b32_e32 v1, s12
	v_bfi_b32 v96, -4, v5, v0
	ds_read_b64 v[0:1], v1
	v_mov_b32_e32 v2, 0x1ce00000
	v_mov_b32_e32 v3, 0x1cc00000
	v_lshlrev_b32_e32 v4, 6, v147
	v_and_b32_e32 v106, 0xc0, v4
	v_cndmask_b32_e64 v136, v2, v3, s[0:1]
	v_lshlrev_b32_e32 v2, 8, v96
	v_lshl_or_b32 v102, v96, 7, v135
	v_or3_b32 v104, v2, v106, v135
	v_ashrrev_i32_e32 v103, 31, v102
	v_ashrrev_i32_e32 v105, 31, v104
	v_lshlrev_b64 v[2:3], 9, v[102:103]
	v_lshlrev_b64 v[4:5], 9, v[104:105]
	s_waitcnt lgkmcnt(0)
	v_lshl_add_u64 v[6:7], v[0:1], 0, v[136:137]
	v_and_b32_e32 v134, 0x78, v158
	s_mov_b64 s[4:5], 0x1d000000
	v_lshlrev_b32_e32 v136, 8, v100
	v_lshl_add_u64 v[0:1], v[0:1], 0, v[4:5]
	v_lshl_add_u64 v[28:29], v[6:7], 0, v[2:3]
	v_lshlrev_b32_e32 v98, 1, v134
	v_mov_b32_e32 v99, v137
	v_lshl_add_u64 v[30:31], v[0:1], 0, s[4:5]
	v_lshl_add_u64 v[0:1], v[28:29], 0, v[136:137]
	s_movk_i32 s9, 0x2000
	v_lshl_add_u64 v[32:33], v[0:1], 0, v[98:99]
	v_lshl_add_u64 v[32:33], v[32:33], 0, v[218:219]
	v_add_co_u32_e32 v12, vcc, s9, v32
	s_movk_i32 s10, 0x4000
	s_nop 0
	v_addc_co_u32_e32 v13, vcc, 0, v33, vcc
	v_add_co_u32_e32 v14, vcc, s10, v32
	s_movk_i32 s11, 0x6000
	s_nop 0
	v_addc_co_u32_e32 v15, vcc, 0, v33, vcc
	v_add_co_u32_e32 v34, vcc, s11, v32
	s_mov_b32 s13, 0x8000
	s_nop 0
	v_addc_co_u32_e32 v35, vcc, 0, v33, vcc
	v_add_co_u32_e32 v36, vcc, s13, v32
	s_mov_b32 s14, 0xa000
	s_nop 0
	v_addc_co_u32_e32 v37, vcc, 0, v33, vcc
	v_add_co_u32_e32 v38, vcc, s14, v32
	s_mov_b32 s15, 0xc000
	s_nop 0
	v_addc_co_u32_e32 v39, vcc, 0, v33, vcc
	v_add_co_u32_e32 v42, vcc, s15, v32
	s_mov_b32 s16, 0xe000
	v_lshl_add_u64 v[2:3], v[30:31], 0, v[136:137]
	v_addc_co_u32_e32 v43, vcc, 0, v33, vcc
	v_lshl_add_u64 v[40:41], v[2:3], 0, v[98:99]
	global_load_dwordx4 v[0:3], v[12:13], off
	global_load_dwordx4 v[4:7], v[14:15], off
	global_load_dwordx4 v[8:11], v[34:35], off
	v_add_co_u32_e32 v42, vcc, s16, v32
	s_mov_b32 s8, 0x3fb8aa3b
	s_nop 0
	v_addc_co_u32_e32 v43, vcc, 0, v33, vcc
	v_add_co_u32_e32 v48, vcc, s9, v40
	v_xor_b32_e32 v136, 0x100, v136
	s_nop 0
	v_addc_co_u32_e32 v49, vcc, 0, v41, vcc
	v_lshl_add_u64 v[28:29], v[28:29], 0, v[136:137]
	v_lshl_add_u64 v[76:77], v[28:29], 0, v[98:99]
	v_lshl_add_u64 v[76:77], v[76:77], 0, v[218:219]
	v_lshl_add_u64 v[28:29], v[30:31], 0, v[136:137]
	v_lshl_add_u64 v[88:89], v[28:29], 0, v[98:99]
	v_mov_b32_e32 v97, 0x12800000
	s_mov_b32 s4, 0xc2ce8ed0
	s_waitcnt vmcnt(0)
	v_mul_f32_e32 v107, 0x43000000, v44
	v_mul_f32_e32 v108, 0x3fb8aa3b, v107
	v_fma_f32 v12, v107, s8, -v108
	v_fmamk_f32 v110, v107, 0x32a5705f, v12
	global_load_dwordx4 v[12:15], v[32:33], off
	global_load_dwordx4 v[36:39], v[40:41], off
	s_nop 0
	global_load_dwordx4 v[44:47], v[48:49], off
	v_add_co_u32_e32 v42, vcc, s10, v40
	v_rndne_f32_e32 v109, v108
	s_nop 0
	v_addc_co_u32_e32 v43, vcc, 0, v41, vcc
	v_add_co_u32_e32 v40, vcc, s11, v40
	v_sub_f32_e32 v99, v108, v109
	s_nop 0
	v_addc_co_u32_e32 v41, vcc, 0, v41, vcc
	v_add_co_u32_e32 v48, vcc, s9, v76
	global_load_dwordx4 v[60:63], v[42:43], off
	global_load_dwordx4 v[64:67], v[40:41], off
	v_addc_co_u32_e32 v49, vcc, 0, v77, vcc
	v_add_co_u32_e32 v50, vcc, s10, v76
	v_add_f32_e32 v99, v99, v110
	s_nop 0
	v_addc_co_u32_e32 v51, vcc, 0, v77, vcc
	v_add_co_u32_e32 v52, vcc, s11, v76
	global_load_dwordx4 v[28:31], v[48:49], off
	global_load_dwordx4 v[40:43], v[50:51], off
	v_addc_co_u32_e32 v53, vcc, 0, v77, vcc
	v_add_co_u32_e32 v54, vcc, s13, v76
	v_exp_f32_e32 v99, v99
	s_nop 0
	v_addc_co_u32_e32 v55, vcc, 0, v77, vcc
	global_load_dwordx4 v[48:51], v[52:53], off
	v_add_co_u32_e32 v52, vcc, s14, v76
	v_cvt_i32_f32_e32 v108, v109
	s_nop 0
	v_addc_co_u32_e32 v53, vcc, 0, v77, vcc
	v_add_co_u32_e32 v54, vcc, s15, v76
	v_mov_b32_e32 v109, 0x10800000
	s_nop 0
	v_addc_co_u32_e32 v55, vcc, 0, v77, vcc
	v_add_co_u32_e32 v90, vcc, s16, v76
	v_addc_co_u32_e32 v91, vcc, 0, v77, vcc
	v_add_co_u32_e32 v92, vcc, s9, v88
	global_load_dwordx4 v[52:55], v[76:77], off
	global_load_dwordx4 v[80:83], v[88:89], off
	v_addc_co_u32_e32 v93, vcc, 0, v89, vcc
	global_load_dwordx4 v[84:87], v[92:93], off
	v_add_co_u32_e32 v90, vcc, s10, v88
	v_cndmask_b32_e64 v138, v97, v109, s[0:1]
	s_nop 0
	v_addc_co_u32_e32 v91, vcc, 0, v89, vcc
	v_add_co_u32_e32 v92, vcc, s11, v88
	v_ldexp_f32 v97, v99, v108
	s_nop 0
	v_addc_co_u32_e32 v93, vcc, 0, v89, vcc
	global_load_dwordx4 v[88:91], v[90:91], off
	s_nop 0
	global_load_dwordx4 v[92:95], v[92:93], off
	v_cmp_ngt_f32_e32 vcc, s4, v107
	s_mov_b32 s4, 0x42b17218
	v_mov_b32_e32 v99, 0x7f800000
	v_cndmask_b32_e32 v97, 0, v97, vcc
	v_cmp_nlt_f32_e32 vcc, s4, v107
	v_and_b32_e32 v165, 48, v101
	v_or_b32_e32 v163, v165, v129
	v_cndmask_b32_e32 v140, v99, v97, vcc
	v_mul_u32_u24_e32 v97, 0x88, v135
	v_lshlrev_b32_e32 v97, 1, v97
	v_add3_u32 v159, v161, v97, v98
	v_or_b32_e32 v98, v106, v163
	s_movk_i32 s4, 0x110
	v_mul_u32_u24_e32 v164, 0x88, v129
	v_ashrrev_i32_e32 v97, 31, v96
	v_lshlrev_b32_e32 v98, 7, v98
	s_mov_b32 s3, 0
	v_mov_b32_e32 v139, v137
	v_mov_b32_e32 v141, v140
	v_mov_b32_e32 v142, v140
	v_mov_b32_e32 v143, v140
	v_mad_u32_u24 v166, v163, s4, v155
	v_lshl_add_u32 v167, v164, 1, v155
	v_sub_u32_e32 v216, v159, v221
	v_sub_u32_e32 v217, v167, v221
	v_add_u32_e32 v216, v216, v220
	v_lshlrev_b64 v[144:145], 13, v[102:103]
	v_lshlrev_b64 v[146:147], 13, v[104:105]
	v_lshlrev_b64 v[148:149], 22, v[96:97]
	v_lshlrev_b32_e32 v150, 16, v100
	v_mov_b32_e32 v151, v137
	s_mov_b32 s13, 30
	s_add_i32 s14, 0, 0x240a0
	v_lshlrev_b32_e32 v152, 1, v98
	s_mov_b32 s15, 0x20000
	s_mov_b32 s16, 0x40000
	s_mov_b32 s17, 0x60000
	s_mov_b32 s18, 0x80000
	s_mov_b32 s19, 0xa0000
	s_mov_b32 s20, 0xc0000
	s_mov_b32 s21, 0xe0000
	s_mov_b32 s22, 0x14800000
	s_mov_b32 s23, 0
	v_mov_b32_e32 v124, v137
	v_mov_b32_e32 v125, v137
	v_mov_b32_e32 v126, v137
	v_mov_b32_e32 v127, v137
	v_mov_b32_e32 v120, v137
	v_mov_b32_e32 v121, v137
	v_mov_b32_e32 v122, v137
	v_mov_b32_e32 v123, v137
	v_mov_b32_e32 v112, v137
	v_mov_b32_e32 v113, v137
	v_mov_b32_e32 v114, v137
	v_mov_b32_e32 v115, v137
	v_mov_b32_e32 v108, v137
	v_mov_b32_e32 v109, v137
	v_mov_b32_e32 v110, v137
	v_mov_b32_e32 v111, v137
	v_mov_b32_e32 v104, v137
	v_mov_b32_e32 v105, v137
	v_mov_b32_e32 v106, v137
	v_mov_b32_e32 v107, v137
	v_mov_b32_e32 v100, v137
	v_mov_b32_e32 v101, v137
	v_mov_b32_e32 v102, v137
	v_mov_b32_e32 v103, v137
	v_mov_b32_e32 v96, v137
	v_mov_b32_e32 v97, v137
	v_mov_b32_e32 v98, v137
	v_mov_b32_e32 v99, v137
	v_mov_b32_e32 v116, v137
	v_mov_b32_e32 v117, v137
	v_mov_b32_e32 v118, v137
	v_mov_b32_e32 v119, v137
	s_branch .LBB0_382
.LBB0_381:
	s_waitcnt lgkmcnt(0)
	s_barrier
	ds_read_b128 v[240:243], v166 offset:34816
	ds_read_b128 v[244:247], v166 offset:34880
	ds_read_b128 v[248:251], v166 offset:34944
	ds_read_b128 v[252:255], v166 offset:35008
	ds_read_b128 v[168:171], v217
	ds_read_b128 v[172:175], v217 offset:4352
	ds_read_b128 v[176:179], v217 offset:8704
	ds_read_b128 v[180:183], v217 offset:13056
	ds_read_b128 v[184:187], v217 offset:17408
	ds_read_b128 v[188:191], v217 offset:21760
	ds_read_b128 v[192:195], v217 offset:26112
	ds_read_b128 v[196:199], v217 offset:30464
	ds_read_b128 v[200:203], v217 offset:64
	ds_read_b128 v[204:207], v217 offset:4416
	ds_read_b128 v[208:211], v217 offset:8768
	v_pk_mul_f32 v[126:127], v[142:143], v[126:127]
	v_pk_mul_f32 v[124:125], v[140:141], v[124:125]
	v_pk_mul_f32 v[122:123], v[142:143], v[122:123]
	v_pk_mul_f32 v[120:121], v[140:141], v[120:121]
	v_pk_mul_f32 v[118:119], v[142:143], v[118:119]
	v_pk_mul_f32 v[116:117], v[140:141], v[116:117]
	v_pk_mul_f32 v[114:115], v[142:143], v[114:115]
	v_pk_mul_f32 v[112:113], v[140:141], v[112:113]
	v_pk_mul_f32 v[110:111], v[142:143], v[110:111]
	v_pk_mul_f32 v[108:109], v[140:141], v[108:109]
	v_pk_mul_f32 v[106:107], v[142:143], v[106:107]
	v_pk_mul_f32 v[104:105], v[140:141], v[104:105]
	v_pk_mul_f32 v[102:103], v[142:143], v[102:103]
	v_pk_mul_f32 v[100:101], v[140:141], v[100:101]
	v_pk_mul_f32 v[98:99], v[142:143], v[98:99]
	v_pk_mul_f32 v[96:97], v[140:141], v[96:97]
	s_waitcnt lgkmcnt(10)
	v_mfma_f32_16x16x32_bf16 v[124:127], v[168:171], v[240:243], v[124:127]
	ds_read_b128 v[168:171], v217 offset:13120
	s_waitcnt lgkmcnt(10)
	v_mfma_f32_16x16x32_bf16 v[120:123], v[172:175], v[240:243], v[120:123]
	ds_read_b128 v[172:175], v217 offset:17472
	s_waitcnt lgkmcnt(10)
	v_mfma_f32_16x16x32_bf16 v[116:119], v[176:179], v[240:243], v[116:119]
	ds_read_b128 v[176:179], v217 offset:21824
	s_waitcnt lgkmcnt(10)
	v_mfma_f32_16x16x32_bf16 v[112:115], v[180:183], v[240:243], v[112:115]
	ds_read_b128 v[180:183], v217 offset:26176
	s_waitcnt lgkmcnt(10)
	v_mfma_f32_16x16x32_bf16 v[108:111], v[184:187], v[240:243], v[108:111]
	ds_read_b128 v[184:187], v217 offset:30528
	s_waitcnt lgkmcnt(10)
	v_mfma_f32_16x16x32_bf16 v[104:107], v[188:191], v[240:243], v[104:107]
	ds_read_b128 v[188:191], v217 offset:128
	s_waitcnt lgkmcnt(10)
	v_mfma_f32_16x16x32_bf16 v[100:103], v[192:195], v[240:243], v[100:103]
	ds_read_b128 v[192:195], v217 offset:4480
	s_waitcnt lgkmcnt(10)
	v_mfma_f32_16x16x32_bf16 v[96:99], v[196:199], v[240:243], v[96:99]
	ds_read_b128 v[196:199], v217 offset:8832
	s_waitcnt lgkmcnt(10)
	v_mfma_f32_16x16x32_bf16 v[124:127], v[200:203], v[244:247], v[124:127]
	ds_read_b128 v[200:203], v217 offset:13184
	s_waitcnt lgkmcnt(10)
	v_mfma_f32_16x16x32_bf16 v[120:123], v[204:207], v[244:247], v[120:123]
	ds_read_b128 v[204:207], v217 offset:17536
	s_waitcnt lgkmcnt(10)
	v_mfma_f32_16x16x32_bf16 v[116:119], v[208:211], v[244:247], v[116:119]
	ds_read_b128 v[208:211], v217 offset:21888
	s_waitcnt lgkmcnt(10)
	v_mfma_f32_16x16x32_bf16 v[112:115], v[168:171], v[244:247], v[112:115]
	ds_read_b128 v[168:171], v217 offset:26240
	s_waitcnt lgkmcnt(10)
	v_mfma_f32_16x16x32_bf16 v[108:111], v[172:175], v[244:247], v[108:111]
	ds_read_b128 v[172:175], v217 offset:30592
	s_waitcnt lgkmcnt(10)
	v_mfma_f32_16x16x32_bf16 v[104:107], v[176:179], v[244:247], v[104:107]
	ds_read_b128 v[176:179], v217 offset:192
	s_waitcnt lgkmcnt(10)
	v_mfma_f32_16x16x32_bf16 v[100:103], v[180:183], v[244:247], v[100:103]
	ds_read_b128 v[180:183], v217 offset:4544
	s_waitcnt lgkmcnt(10)
	v_mfma_f32_16x16x32_bf16 v[96:99], v[184:187], v[244:247], v[96:99]
	ds_read_b128 v[184:187], v217 offset:26304
	s_waitcnt lgkmcnt(10)
	v_mfma_f32_16x16x32_bf16 v[124:127], v[188:191], v[248:251], v[124:127]
	ds_read_b128 v[188:191], v217 offset:21952
	s_waitcnt lgkmcnt(10)
	v_mfma_f32_16x16x32_bf16 v[120:123], v[192:195], v[248:251], v[120:123]
	ds_read_b128 v[192:195], v217 offset:17600
	s_waitcnt lgkmcnt(10)
	v_mfma_f32_16x16x32_bf16 v[116:119], v[196:199], v[248:251], v[116:119]
	ds_read_b128 v[196:199], v217 offset:13248
	s_waitcnt lgkmcnt(10)
	v_mfma_f32_16x16x32_bf16 v[112:115], v[200:203], v[248:251], v[112:115]
	ds_read_b128 v[200:203], v217 offset:8896
	s_waitcnt lgkmcnt(10)
	v_mfma_f32_16x16x32_bf16 v[108:111], v[204:207], v[248:251], v[108:111]
	ds_read_b128 v[204:207], v217 offset:30656
	s_waitcnt lgkmcnt(10)
	v_mfma_f32_16x16x32_bf16 v[104:107], v[208:211], v[248:251], v[104:107]
	s_waitcnt lgkmcnt(9)
	v_mfma_f32_16x16x32_bf16 v[100:103], v[168:171], v[248:251], v[100:103]
	s_waitcnt lgkmcnt(8)
	v_mfma_f32_16x16x32_bf16 v[212:215], v[172:175], v[248:251], v[96:99]
	s_waitcnt lgkmcnt(7)
	v_mfma_f32_16x16x32_bf16 v[124:127], v[176:179], v[252:255], v[124:127]
	s_waitcnt lgkmcnt(6)
	v_mfma_f32_16x16x32_bf16 v[120:123], v[180:183], v[252:255], v[120:123]
	s_waitcnt lgkmcnt(5)
	v_mfma_f32_16x16x32_bf16 v[96:99], v[184:187], v[252:255], v[100:103]
	s_waitcnt lgkmcnt(4)
	v_mfma_f32_16x16x32_bf16 v[100:103], v[188:191], v[252:255], v[104:107]
	s_waitcnt lgkmcnt(3)
	v_mfma_f32_16x16x32_bf16 v[104:107], v[192:195], v[252:255], v[108:111]
	s_waitcnt lgkmcnt(2)
	v_mfma_f32_16x16x32_bf16 v[108:111], v[196:199], v[252:255], v[112:115]
	s_waitcnt lgkmcnt(1)
	v_mfma_f32_16x16x32_bf16 v[112:115], v[200:203], v[252:255], v[116:119]
	s_waitcnt lgkmcnt(0)
	v_mfma_f32_16x16x32_bf16 v[116:119], v[204:207], v[252:255], v[212:215]
	s_add_i32 s23, s23, 1
	s_add_i32 s3, s3, 2
	s_add_i32 s13, s13, -2
	s_cmp_lg_u32 s3, 34
	s_cbranch_scc0 .LBB0_406
.LBB0_382:
	s_lshl_b32 s24, s23, 1
	s_cmp_lg_u32 s3, 0
	s_cselect_b64 s[8:9], -1, 0
	s_and_b64 vcc, exec, s[8:9]
	s_waitcnt lgkmcnt(0)
	s_barrier
	s_waitcnt vmcnt(8)
	s_cbranch_vccz .LBB0_404
	s_and_saveexec_b64 s[4:5], s[6:7]
	s_xor_b64 s[4:5], exec, s[4:5]
	s_sub_i32 s10, 33, s24
	s_or_saveexec_b64 s[4:5], s[4:5]
	v_mov_b32_e32 v136, s10
	s_xor_b64 exec, exec, s[4:5]
	s_add_i32 s10, s3, -2
	v_mov_b32_e32 v136, s10
	s_or_b64 exec, exec, s[4:5]
	s_cbranch_execnz .LBB0_389

.LBB0_391:
	s_cmp_lg_u32 s3, 32
	s_cselect_b64 s[10:11], -1, 0
	s_cmp_eq_u32 s3, 32
	ds_write_b128 v216, v[12:15]
	ds_write_b128 v216, v[0:3] offset:4352
	ds_write_b128 v216, v[4:7] offset:8704
	ds_write_b128 v216, v[8:11] offset:13056
	ds_write_b128 v159, v[36:39] offset:34816
	ds_write_b128 v159, v[44:47] offset:39168
	ds_write_b128 v159, v[60:63] offset:43520
	ds_write_b128 v159, v[64:67] offset:47872
	s_cbranch_scc1 .LBB0_393
	v_mov_b32_e32 v0, s12
	ds_read_b64 v[0:1], v0
	s_add_i32 s25, s13, 1
	v_mov_b32_e32 v2, s3
	v_mov_b32_e32 v3, s25
	v_cndmask_b32_e64 v4, v3, v2, s[0:1]
	s_waitcnt lgkmcnt(0)
	v_lshl_add_u64 v[2:3], v[0:1], 0, v[138:139]
	v_lshl_add_u64 v[2:3], v[2:3], 0, v[144:145]
	v_lshlrev_b32_e32 v136, 8, v4
	v_lshl_add_u64 v[2:3], v[2:3], 0, v[136:137]
	v_lshlrev_b32_e32 v4, 1, v134
	v_mov_b32_e32 v5, v137
	v_lshl_add_u64 v[0:1], v[0:1], 0, v[146:147]
	v_lshl_add_u64 v[24:25], v[2:3], 0, v[4:5]
	v_lshl_add_u64 v[24:25], v[24:25], 0, v[222:223]
	v_lshl_add_u64 v[0:1], v[0:1], 0, v[136:137]
	v_lshl_add_u64 v[60:61], v[0:1], 0, v[4:5]
	v_add_co_u32_e32 v0, vcc, s15, v24
	s_nop 1
	v_addc_co_u32_e32 v1, vcc, 0, v25, vcc
	v_add_co_u32_e32 v4, vcc, s16, v24
	global_load_dwordx4 v[12:15], v[24:25], off
	s_nop 0
	global_load_dwordx4 v[0:3], v[0:1], off
	v_addc_co_u32_e32 v5, vcc, 0, v25, vcc
	v_add_co_u32_e32 v8, vcc, s17, v24
	s_nop 1
	v_addc_co_u32_e32 v9, vcc, 0, v25, vcc
	v_add_co_u32_e32 v16, vcc, s18, v24
	global_load_dwordx4 v[4:7], v[4:5], off
	s_nop 0
	global_load_dwordx4 v[8:11], v[8:9], off
	v_addc_co_u32_e32 v17, vcc, 0, v25, vcc
	v_add_co_u32_e32 v20, vcc, s19, v24
	s_nop 1
	v_addc_co_u32_e32 v21, vcc, 0, v25, vcc
	v_add_co_u32_e32 v26, vcc, s20, v24
	s_nop 0
	v_addc_co_u32_e32 v27, vcc, 0, v25, vcc
	v_add_co_u32_e32 v32, vcc, s21, v24
	s_nop 1
	v_addc_co_u32_e32 v33, vcc, 0, v25, vcc
	v_add_co_u32_e32 v36, vcc, s22, v60
	s_nop 0
	v_addc_co_u32_e32 v37, vcc, 0, v61, vcc
	v_add_co_u32_e32 v44, vcc, 0x14820000, v60
	s_nop 1
	v_addc_co_u32_e32 v45, vcc, 0, v61, vcc
	v_add_co_u32_e32 v62, vcc, 0x14840000, v60
	global_load_dwordx4 v[36:39], v[36:37], off
	s_nop 0
	global_load_dwordx4 v[44:47], v[44:45], off
	v_addc_co_u32_e32 v63, vcc, 0, v61, vcc
	v_add_co_u32_e32 v64, vcc, 0x14860000, v60
	s_nop 1
	v_addc_co_u32_e32 v65, vcc, 0, v61, vcc
	global_load_dwordx4 v[60:63], v[62:63], off
	s_nop 0
	global_load_dwordx4 v[64:67], v[64:65], off
.LBB0_393:
	s_waitcnt lgkmcnt(0)
	s_barrier
	ds_read_b128 v[240:243], v166 offset:34816
	ds_read_b128 v[244:247], v166 offset:34880
	ds_read_b128 v[248:251], v166 offset:34944
	ds_read_b128 v[252:255], v166 offset:35008
	ds_read_b128 v[168:171], v217
	ds_read_b128 v[172:175], v217 offset:4352
	ds_read_b128 v[176:179], v217 offset:8704
	ds_read_b128 v[180:183], v217 offset:13056
	ds_read_b128 v[184:187], v217 offset:17408
	ds_read_b128 v[188:191], v217 offset:21760
	ds_read_b128 v[192:195], v217 offset:26112
	ds_read_b128 v[196:199], v217 offset:30464
	ds_read_b128 v[200:203], v217 offset:64
	ds_read_b128 v[204:207], v217 offset:4416
	ds_read_b128 v[208:211], v217 offset:8768
	v_pk_mul_f32 v[126:127], v[142:143], v[126:127]
	v_pk_mul_f32 v[124:125], v[140:141], v[124:125]
	v_pk_mul_f32 v[122:123], v[142:143], v[122:123]
	v_pk_mul_f32 v[120:121], v[140:141], v[120:121]
	v_pk_mul_f32 v[114:115], v[142:143], v[114:115]
	v_pk_mul_f32 v[112:113], v[140:141], v[112:113]
	v_pk_mul_f32 v[110:111], v[142:143], v[110:111]
	v_pk_mul_f32 v[108:109], v[140:141], v[108:109]
	v_pk_mul_f32 v[106:107], v[142:143], v[106:107]
	v_pk_mul_f32 v[104:105], v[140:141], v[104:105]
	v_pk_mul_f32 v[102:103], v[142:143], v[102:103]
	v_pk_mul_f32 v[100:101], v[140:141], v[100:101]
	v_pk_mul_f32 v[98:99], v[142:143], v[98:99]
	v_pk_mul_f32 v[96:97], v[140:141], v[96:97]
	v_pk_mul_f32 v[118:119], v[142:143], v[118:119]
	v_pk_mul_f32 v[116:117], v[140:141], v[116:117]
	s_waitcnt lgkmcnt(10)
	v_mfma_f32_16x16x32_bf16 v[124:127], v[168:171], v[240:243], v[124:127]
	ds_read_b128 v[168:171], v217 offset:13120
	s_waitcnt lgkmcnt(10)
	v_mfma_f32_16x16x32_bf16 v[120:123], v[172:175], v[240:243], v[120:123]
	ds_read_b128 v[172:175], v217 offset:17472
	s_waitcnt lgkmcnt(10)
	v_mfma_f32_16x16x32_bf16 v[112:115], v[176:179], v[240:243], v[112:115]
	ds_read_b128 v[176:179], v217 offset:21824
	s_waitcnt lgkmcnt(10)
	v_mfma_f32_16x16x32_bf16 v[108:111], v[180:183], v[240:243], v[108:111]
	ds_read_b128 v[180:183], v217 offset:26176
	s_waitcnt lgkmcnt(10)
	v_mfma_f32_16x16x32_bf16 v[104:107], v[184:187], v[240:243], v[104:107]
	ds_read_b128 v[184:187], v217 offset:30528
	s_waitcnt lgkmcnt(10)
	v_mfma_f32_16x16x32_bf16 v[100:103], v[188:191], v[240:243], v[100:103]
	ds_read_b128 v[188:191], v217 offset:128
	s_waitcnt lgkmcnt(10)
	v_mfma_f32_16x16x32_bf16 v[96:99], v[192:195], v[240:243], v[96:99]
	ds_read_b128 v[192:195], v217 offset:4480
	s_waitcnt lgkmcnt(10)
	v_mfma_f32_16x16x32_bf16 v[116:119], v[196:199], v[240:243], v[116:119]
	ds_read_b128 v[196:199], v217 offset:8832
	s_waitcnt lgkmcnt(10)
	v_mfma_f32_16x16x32_bf16 v[124:127], v[200:203], v[244:247], v[124:127]
	ds_read_b128 v[200:203], v217 offset:13184
	s_waitcnt lgkmcnt(10)
	v_mfma_f32_16x16x32_bf16 v[120:123], v[204:207], v[244:247], v[120:123]
	ds_read_b128 v[204:207], v217 offset:17536
	s_waitcnt lgkmcnt(10)
	v_mfma_f32_16x16x32_bf16 v[112:115], v[208:211], v[244:247], v[112:115]
	ds_read_b128 v[208:211], v217 offset:21888
	s_waitcnt lgkmcnt(10)
	v_mfma_f32_16x16x32_bf16 v[108:111], v[168:171], v[244:247], v[108:111]
	ds_read_b128 v[168:171], v217 offset:26240
	s_waitcnt lgkmcnt(10)
	v_mfma_f32_16x16x32_bf16 v[104:107], v[172:175], v[244:247], v[104:107]
	ds_read_b128 v[172:175], v217 offset:30592
	s_waitcnt lgkmcnt(10)
	v_mfma_f32_16x16x32_bf16 v[100:103], v[176:179], v[244:247], v[100:103]
	ds_read_b128 v[176:179], v217 offset:192
	s_waitcnt lgkmcnt(10)
	v_mfma_f32_16x16x32_bf16 v[96:99], v[180:183], v[244:247], v[96:99]
	ds_read_b128 v[180:183], v217 offset:4544
	s_waitcnt lgkmcnt(10)
	v_mfma_f32_16x16x32_bf16 v[116:119], v[184:187], v[244:247], v[116:119]
	ds_read_b128 v[184:187], v217 offset:8896
	s_waitcnt lgkmcnt(10)
	v_mfma_f32_16x16x32_bf16 v[124:127], v[188:191], v[248:251], v[124:127]
	ds_read_b128 v[188:191], v217 offset:13248
	s_waitcnt lgkmcnt(10)
	v_mfma_f32_16x16x32_bf16 v[120:123], v[192:195], v[248:251], v[120:123]
	ds_read_b128 v[192:195], v217 offset:17600
	s_waitcnt lgkmcnt(10)
	v_mfma_f32_16x16x32_bf16 v[112:115], v[196:199], v[248:251], v[112:115]
	ds_read_b128 v[196:199], v217 offset:21952
	s_waitcnt lgkmcnt(10)
	v_mfma_f32_16x16x32_bf16 v[108:111], v[200:203], v[248:251], v[108:111]
	ds_read_b128 v[200:203], v217 offset:26304
	s_waitcnt lgkmcnt(10)
	v_mfma_f32_16x16x32_bf16 v[104:107], v[204:207], v[248:251], v[104:107]
	ds_read_b128 v[204:207], v217 offset:30656
	s_waitcnt lgkmcnt(10)
	v_mfma_f32_16x16x32_bf16 v[100:103], v[208:211], v[248:251], v[100:103]
	s_waitcnt lgkmcnt(9)
	v_mfma_f32_16x16x32_bf16 v[96:99], v[168:171], v[248:251], v[96:99]
	s_waitcnt lgkmcnt(8)
	v_mfma_f32_16x16x32_bf16 v[212:215], v[172:175], v[248:251], v[116:119]
	s_waitcnt lgkmcnt(0)
	s_barrier
	s_waitcnt vmcnt(4)
	v_mfma_f32_16x16x32_bf16 v[124:127], v[176:179], v[252:255], v[124:127]
	v_mfma_f32_16x16x32_bf16 v[120:123], v[180:183], v[252:255], v[120:123]
	v_mfma_f32_16x16x32_bf16 v[116:119], v[184:187], v[252:255], v[112:115]
	v_mfma_f32_16x16x32_bf16 v[112:115], v[188:191], v[252:255], v[108:111]
	v_mfma_f32_16x16x32_bf16 v[108:111], v[192:195], v[252:255], v[104:107]
	v_mfma_f32_16x16x32_bf16 v[104:107], v[196:199], v[252:255], v[100:103]
	v_mfma_f32_16x16x32_bf16 v[100:103], v[200:203], v[252:255], v[96:99]
	v_mfma_f32_16x16x32_bf16 v[96:99], v[204:207], v[252:255], v[212:215]
	s_and_b64 vcc, exec, s[8:9]
	s_cbranch_vccz .LBB0_405
	s_and_saveexec_b64 s[8:9], s[6:7]
	s_xor_b64 s[8:9], exec, s[8:9]
	s_or_b32 s24, s24, 1
	s_sub_i32 s25, 33, s24
	s_or_saveexec_b64 s[8:9], s[8:9]
	v_mov_b32_e32 v136, s25
	s_xor_b64 exec, exec, s[8:9]
	s_add_i32 s24, s3, -1
	v_mov_b32_e32 v136, s24
	s_or_b64 exec, exec, s[8:9]
	s_add_i32 s8, s3, 1
	s_cbranch_execnz .LBB0_400

.LBB0_402:
	s_andn2_b64 vcc, exec, s[10:11]
	ds_write_b128 v216, v[52:55]
	ds_write_b128 v216, v[28:31] offset:4352
	ds_write_b128 v216, v[40:43] offset:8704
	ds_write_b128 v216, v[48:51] offset:13056
	ds_write_b128 v159, v[80:83] offset:34816
	ds_write_b128 v159, v[84:87] offset:39168
	ds_write_b128 v159, v[88:91] offset:43520
	ds_write_b128 v159, v[92:95] offset:47872
	s_cbranch_vccnz .LBB0_381
	v_mov_b32_e32 v28, s12
	ds_read_b64 v[28:29], v28
	v_mov_b32_e32 v30, s13
	v_mov_b32_e32 v31, s8
	v_cndmask_b32_e64 v30, v30, v31, s[0:1]
	v_lshlrev_b32_e32 v136, 8, v30
	s_waitcnt lgkmcnt(0)
	v_lshl_add_u64 v[30:31], v[28:29], 0, v[138:139]
	v_lshl_add_u64 v[30:31], v[30:31], 0, v[144:145]
	v_lshl_add_u64 v[30:31], v[30:31], 0, v[136:137]
	v_lshlrev_b32_e32 v40, 1, v134
	v_mov_b32_e32 v41, v137
	v_lshl_add_u64 v[28:29], v[28:29], 0, v[146:147]
	v_lshl_add_u64 v[72:73], v[30:31], 0, v[40:41]
	v_lshl_add_u64 v[72:73], v[72:73], 0, v[222:223]
	v_lshl_add_u64 v[28:29], v[28:29], 0, v[136:137]
	v_lshl_add_u64 v[88:89], v[28:29], 0, v[40:41]
	v_add_co_u32_e32 v28, vcc, s15, v72
	s_nop 1
	v_addc_co_u32_e32 v29, vcc, 0, v73, vcc
	v_add_co_u32_e32 v40, vcc, s16, v72
	global_load_dwordx4 v[52:55], v[72:73], off
	s_nop 0
	global_load_dwordx4 v[28:31], v[28:29], off
	v_addc_co_u32_e32 v41, vcc, 0, v73, vcc
	v_add_co_u32_e32 v48, vcc, s17, v72
	s_nop 1
	v_addc_co_u32_e32 v49, vcc, 0, v73, vcc
	v_add_co_u32_e32 v56, vcc, s18, v72
	global_load_dwordx4 v[40:43], v[40:41], off
	s_nop 0
	global_load_dwordx4 v[48:51], v[48:49], off
	v_addc_co_u32_e32 v57, vcc, 0, v73, vcc
	v_add_co_u32_e32 v68, vcc, s19, v72
	s_nop 1
	v_addc_co_u32_e32 v69, vcc, 0, v73, vcc
	v_add_co_u32_e32 v74, vcc, s20, v72
	s_nop 0
	v_addc_co_u32_e32 v75, vcc, 0, v73, vcc
	v_add_co_u32_e32 v76, vcc, s21, v72
	s_nop 1
	v_addc_co_u32_e32 v77, vcc, 0, v73, vcc
	v_add_co_u32_e32 v80, vcc, s22, v88
	s_nop 0
	v_addc_co_u32_e32 v81, vcc, 0, v89, vcc
	v_add_co_u32_e32 v84, vcc, 0x14820000, v88
	s_nop 1
	v_addc_co_u32_e32 v85, vcc, 0, v89, vcc
	v_add_co_u32_e32 v90, vcc, 0x14840000, v88
	global_load_dwordx4 v[80:83], v[80:81], off
	s_nop 0
	global_load_dwordx4 v[84:87], v[84:85], off
	v_addc_co_u32_e32 v91, vcc, 0, v89, vcc
	v_add_co_u32_e32 v92, vcc, 0x14860000, v88
	s_nop 1
	v_addc_co_u32_e32 v93, vcc, 0, v89, vcc
	global_load_dwordx4 v[88:91], v[90:91], off
	s_nop 0
	global_load_dwordx4 v[92:95], v[92:93], off
	s_branch .LBB0_381
